# v57 + up-projection phase: workgroup rotation of the kv / pooling GEMMs changed (+52 instead of +204/+220) so no workgroup carries q + 2 kv + pooling tiles
# speedup vs baseline: 1.0024x; 1.0024x over previous
;     __device__ __forceinline__ unsigned code(int i, unsigned& ko_) const { Unit u; u.pm = 0; u.pn = 0; u.ko = 0; u.nk = 0; u.ks = 0; const bool ok = next(i, u); ko_ = (unsigned)u.ko; return ok ? (0x80000000u | ((unsigned)u.nk << 16) | ((unsigned)u.pm << 8) | (unsigned)u.pn) : 0u; }
; #define GEMM(g, S, E) pg8::gemm_phase<decltype(E), decltype(S), true, true>((LAS unsigned char*)lds, g, S, E, wv)
;     __host__ __device__ __forceinline__ bool next(int i, Unit& u) const {
;         const long L = (long)i * G + c; if (L >= nwg) return false;
;         int wgid = (int)L; { const int q = nwg / NXCD, r = nwg % NXCD, xcd = wgid % NXCD, off = wgid / NXCD; wgid = (xcd < r ? xcd * (q + 1) : r * (q + 1) + (xcd - r) * q) + off; }
;         const int nig = WGM * nN, gid = wgid / nig, fm = gid * WGM, gsz = (nM - fm) < WGM ? (nM - fm) : WGM;
;         u.pm = fm + ((wgid % nig) % gsz); u.pn = (wgid % nig) / gsz; u.ko = 0; u.nk = nk; return true;
;     }
;         const int pair = (K / 64) / (nks_ / 2); t1 = ((pair / 2 + 1) / 2) * 2; t2 = pair - t1; }
;     __device__ __forceinline__ unsigned code(int i, unsigned& ko_) const {
;         const int L = i * lat.G + lat.c; if (L < nlat) return lat.code(i, ko_);
;         const int Lp = L - nlat; if (Lp >= nsp) { ko_ = 0u; return 0u; }
;         const int r = Lp / nks, ks = Lp % nks; ko_ = (unsigned)(((ks >> 1) * (t1 + t2) + (ks & 1) * t1) * 64);
;         return 0x80000000u | ((unsigned)ks << 24) | ((unsigned)((ks & 1) ? t2 : t1) << 16) | ((unsigned)(64 + (r & 3)) << 8) | (unsigned)(r >> 2);
; __global__ void __launch_bounds__(512, 2) fwd_kernel(Params p) {
;     ...
;         { PH_BEGIN pg8::Gemm g{WSP(bf16_t, WS_BQN), (const bf16_t*)(wl + W_UQ), R, 768, 512, 512}; S.init(R, 768, G, bid, 512); EpiUq E{WSP(bf16_t, WS_QB), WSP(float, WS_TAB) + 4096, WSP(float, WS_TAB) + 4096 + 1024}; GEMM(g, S, E); }
;         { PH_BEGIN pg8::Gemm g{WSP(bf16_t, WS_BKVN), (const bf16_t*)(wl + W_UKV), R, 1024, 256, 256}; S.init(R, 1024, G, (bid + 204) % G, 256); EpiUkv E{WSP(bf16_t, WS_KB), WSP(bf16_t, WS_VB)}; GEMM(g, S, E); }
;         { PH_BEGIN pg8::Gemm g{WSP(bf16_t, WS_POOL), (const bf16_t*)(wl + W_PL), R, 512, 512, 512}; S.init(R, 512, G, (bid + 220) % G, 512); EpiPool E{WSP(bf16_t, WS_Y)}; GEMM(g, S, E); }
.LBB0_250:
	s_or_b64 exec, exec, s[36:37]
	s_cmpk_lt_i32 s92, 0xbb0
	s_cselect_b64 s[0:1], -1, 0
	v_writelane_b32 v254, s0, 6
	s_ashr_i32 s90, s92, 31
	s_bfe_u32 s2, s92, 0x20001
	v_writelane_b32 v254, s1, 7
	s_lshr_b32 s0, s90, 29
	s_and_b32 s3, s92, 1
	s_add_i32 s0, s92, s0
	s_mul_i32 s2, s2, 22
	s_mul_i32 s4, s3, 12
	s_ashr_i32 s17, s0, 3
	s_and_b32 s0, s0, -8
	s_and_b32 s1, s92, 7
	s_add_i32 s2, s2, s4
	s_sub_i32 s18, s92, s0
	s_and_b32 s0, s92, 0x7fffff00
	s_lshl_b32 s2, s2, 6
	s_lshl_b32 s1, s1, 24
	s_cmp_eq_u32 s3, 0
	s_mov_b32 s3, 0xc0000
	s_cselect_b32 s3, s3, 0xa0000
	s_lshl_b32 s4, s92, 5
	s_and_b32 s4, s4, 0x300
	s_bfe_u32 s5, s92, 0x30005
	s_or_b32 s4, s5, s4
	s_or_b32 s1, s4, s1
	s_or_b32 s3, s1, s3
	s_or_b32 s3, s3, 0x80004000
	s_lshl_b32 s4, s18, 6
	s_lshl_b32 s6, s92, 9
	s_lshl_b32 s5, s92, 2
	s_cmpk_lt_i32 s5, 0x400
	v_writelane_b32 v254, s5, 8
	s_cselect_b64 s[8:9], -1, 0
	v_writelane_b32 v254, s8, 9
	s_lshl_b32 s7, s92, 24
	s_and_b32 s7, s7, 0x3000000
	v_writelane_b32 v254, s9, 10
	s_lshl_b32 s8, s92, 6
	s_bfe_u32 s10, s92, 0x40004
	s_and_b32 s9, s8, 0x300
	s_or_b32 s7, s7, s10
	s_or_b32 s7, s7, s9
	s_add_i32 s5, s92, 0xfffffd00
	v_writelane_b32 v254, s6, 11
	s_and_b32 s6, s6, 0x600
	s_or_b32 s7, s7, 0x80084000
	s_cmpk_lt_i32 s92, 0xcc
	s_cselect_b64 s[10:11], -1, 0
	s_lshl_b32 s12, s94, 8
	s_add_i32 s59, s12, 0
	s_lshl_b32 s12, s94, 12
	v_writelane_b32 v254, s10, 12
	s_add_i32 s12, s12, 0
	s_add_i32 s12, s12, 0x14800
	v_writelane_b32 v254, s11, 13
	v_writelane_b32 v254, s12, 14
	s_add_i32 s12, s92, 0xfffffe00
	s_mul_i32 s9, s18, 25
	v_writelane_b32 v254, s12, 15
	s_lshl_b32 s12, s92, 8
	s_add_i32 s9, s9, 4
	s_add_i32 s10, s92, 0x34
	s_add_i32 s11, s92, 0x34
	s_add_i32 s95, s59, 0x10000
	s_lshl_b32 s19, s94, 5
	s_add_i32 s59, s59, 0x14000
	s_and_b32 s12, s12, 0x700
	s_or_b32 s1, s1, 0x80044000
	v_writelane_b32 v254, s12, 16
	s_cmp_lt_i32 s18, 0
	s_movk_i32 s12, 0x177
	v_writelane_b32 v254, s1, 17
	s_mul_i32 s1, s18, 0x41
	s_cselect_b32 s12, s12, 0x176
	s_mul_i32 s12, s18, s12
	s_cselect_b32 s1, s1, s4
	s_movk_i32 s4, 0x61
	s_cselect_b32 s4, s4, 0x60
	s_add_i32 s12, s12, s17
	s_mul_hi_i32 s13, s12, 0x2e8ba2e9
	s_lshr_b32 s14, s13, 31
	s_ashr_i32 s13, s13, 6
	s_add_i32 s13, s13, s14
	s_mul_i32 s14, s13, 0x160
	s_lshl_b32 s13, s13, 3
	s_sub_i32 s15, 0x44, s13
	s_min_u32 s15, s15, 8
	s_sub_i32 s12, s12, s14
	s_cmpk_eq_i32 s0, 0x200
	s_cselect_b32 s2, s2, 0
	s_cselect_b32 s3, s3, 0
	s_add_i32 s0, s1, s17
	s_ashr_i32 s1, s0, 31
	s_lshr_b32 s1, s1, 26
	s_add_i32 s1, s0, s1
	s_and_b32 s14, s1, 0xffc0
	s_sub_i32 s0, s0, s14
	s_bfe_i32 s14, s0, 0x80000
	s_bfe_u32 s14, s14, 0x3000c
	s_add_i32 s14, s0, s14
	s_bfe_i32 s16, s14, 0x80000
	s_and_b32 s14, s14, 0xf8
	s_sub_i32 s0, s0, s14
	s_sext_i32_i8 s0, s0
	s_lshl_b32 s1, s1, 5
	s_sext_i32_i16 s16, s16
	s_and_b32 s1, s1, 0xfffff800
	s_lshl_b32 s0, s0, 8
	s_ashr_i32 s14, s16, 3
	s_add_i32 s0, s0, s1
	s_or_b32 s0, s0, s14
	s_or_b32 s14, s0, 0x80580000
	s_cmpk_lt_u32 s5, 0xc0
	s_mul_i32 s4, s18, s4
	s_cselect_b32 s1, s6, 0
	s_cselect_b32 s5, s7, 0
	s_add_i32 s4, s4, s17
	s_mul_hi_i32 s6, s4, 0x2aaaaaab
	s_lshr_b32 s7, s6, 31
	s_ashr_i32 s6, s6, 4
	s_add_i32 s6, s6, s7
	s_mul_i32 s7, s6, 0x60
	s_sub_i32 s4, s4, s7
	s_bfe_i32 s7, s4, 0x80000
	s_bfe_u32 s7, s7, 0x3000c
	s_add_i32 s7, s4, s7
	s_bfe_i32 s16, s7, 0x80000
	s_and_b32 s7, s7, 0xf8
	s_sub_i32 s4, s4, s7
	s_sext_i32_i8 s4, s4
	s_sext_i32_i16 s16, s16
	s_lshl_b32 s6, s6, 11
	s_lshl_b32 s4, s4, 8
	s_ashr_i32 s7, s16, 3
	s_add_i32 s4, s4, s6
	s_or_b32 s4, s4, s7
	s_or_b32 s4, s4, 0x80200000
	s_cmp_lt_i32 s18, 4
	s_mul_i32 s6, s18, 26
	s_cselect_b32 s6, s6, s9
	s_add_i32 s6, s6, s17
	s_mul_hi_i32 s7, s6, 0x2aaaaaab
	s_lshr_b32 s9, s7, 31
	s_ashr_i32 s7, s7, 2
	s_add_i32 s7, s7, s9
	s_lshl_b32 s9, s7, 3
	s_sub_i32 s16, 0x44, s9
	s_mul_i32 s7, s7, 24
	s_min_u32 s16, s16, 8
; #define GEMM(g, S, E) pg8::gemm_phase<decltype(E), decltype(S), true, true>((LAS unsigned char*)lds, g, S, E, wv)
; #define PH_BEGIN KParams kp = kargs(); unsigned char* ws = kp->ws; (void)ws; const int G = gridDim.x, bid = blockIdx.x; (void)G; (void)bid; \
;     const unsigned char* wl = ws + WS_W + (size_t)layer * W_LAYER; (void)wl; const float* mod = WSP(float, WS_MOD) + (size_t)layer * 5 * MODW; (void)mod; pg8::StaticOrder S; (void)S;
;     __host__ __device__ __forceinline__ bool next(int i, Unit& u) const {
;         const long L = (long)i * G + c; if (L >= nwg) return false;
;         int wgid = (int)L; { const int q = nwg / NXCD, r = nwg % NXCD, xcd = wgid % NXCD, off = wgid / NXCD; wgid = (xcd < r ? xcd * (q + 1) : r * (q + 1) + (xcd - r) * q) + off; }
;         const int nig = WGM * nN, gid = wgid / nig, fm = gid * WGM, gsz = (nM - fm) < WGM ? (nM - fm) : WGM;
;         u.pm = fm + ((wgid % nig) % gsz); u.pn = (wgid % nig) / gsz; u.ko = 0; u.nk = nk; return true;
;     }
; __global__ void __launch_bounds__(512, 2) fwd_kernel(Params p) {
;     ...
;         { PH_BEGIN pg8::Gemm g{WSP(bf16_t, WS_BQN), (const bf16_t*)(wl + W_UQ), R, 768, 512, 512}; S.init(R, 768, G, bid, 512); EpiUq E{WSP(bf16_t, WS_QB), WSP(float, WS_TAB) + 4096, WSP(float, WS_TAB) + 4096 + 1024}; GEMM(g, S, E); }
;         { PH_BEGIN pg8::Gemm g{WSP(bf16_t, WS_BKVN), (const bf16_t*)(wl + W_UKV), R, 1024, 256, 256}; S.init(R, 1024, G, (bid + 204) % G, 256); EpiUkv E{WSP(bf16_t, WS_KB), WSP(bf16_t, WS_VB)}; GEMM(g, S, E); }
;         { PH_BEGIN pg8::Gemm g{WSP(bf16_t, WS_POOL), (const bf16_t*)(wl + W_PL), R, 512, 512, 512}; S.init(R, 512, G, (bid + 220) % G, 512); EpiPool E{WSP(bf16_t, WS_Y)}; GEMM(g, S, E); }
	s_sub_i32 s6, s6, s7
	s_or_b32 s0, s0, 0x80200000
	v_writelane_b32 v254, s17, 18
	s_cmpk_lt_i32 s92, 0x300
	v_writelane_b32 v254, s0, 19
	s_cselect_b32 s0, 0, s1
	v_writelane_b32 v254, s0, 20
	v_cvt_f32_ubyte0_e32 v1, s15
	v_cvt_f32_i32_e32 v0, s12
	v_writelane_b32 v254, s1, 21
	s_cselect_b32 s0, s4, s5
	v_writelane_b32 v254, s0, 22
	v_writelane_b32 v254, s18, 23
	s_lshr_b32 s0, s18, 31
	v_writelane_b32 v254, s0, 24
	s_mul_i32 s4, s94, 0x21000
	v_writelane_b32 v254, s4, 25
	s_cmpk_lt_i32 s92, 0x200
	v_writelane_b32 v254, s19, 26
	s_mul_hi_u32 s4, s19, 0x1080
	s_cselect_b64 s[0:1], -1, 0
	v_writelane_b32 v254, s4, 27
	v_rcp_iflag_f32_e32 v2, v1
	v_writelane_b32 v254, s0, 28
	s_mov_b64 s[4:5], -1
	s_movk_i32 s73, 0x600
	v_writelane_b32 v254, s1, 29
	s_and_b64 s[0:1], s[0:1], exec
	s_cselect_b32 s0, 0, s2
	v_writelane_b32 v254, s0, 30
	v_mul_f32_e32 v2, v0, v2
	v_trunc_f32_e32 v2, v2
	v_writelane_b32 v254, s1, 31
	s_cselect_b32 s0, s14, s3
	v_writelane_b32 v254, s0, 32
	s_cselect_b32 s0, s14, 0
	v_fma_f32 v0, -v2, v1, v0
	v_cvt_i32_f32_e32 v2, v2
	v_writelane_b32 v254, s0, 33
	s_and_b32 s0, s92, 7
	s_lshl_b32 s0, s0, 3
	s_lshr_b32 s1, s92, 6
	s_add_i32 s0, s0, s1
	s_lshl_b32 s0, s0, 8
	s_bfe_u32 s1, s92, 0x30003
	s_or_b32 s0, s0, s1
	s_or_b32 s0, s0, 0x80580000
	v_writelane_b32 v254, s0, 32
	v_writelane_b32 v254, s0, 33
	s_ashr_i32 s0, s12, 30
	s_or_b32 s2, s0, 1
	v_cmp_ge_f32_e64 s[0:1], |v0|, v1
	s_and_b64 s[0:1], s[0:1], exec
	s_cselect_b32 s0, s2, 0
	v_readfirstlane_b32 s1, v2
	s_add_i32 s0, s1, s0
	v_cvt_f32_ubyte0_e32 v1, s16
	s_sext_i32_i16 s1, s0
	s_mul_i32 s0, s0, s15
	v_cvt_f32_i32_e32 v0, s6
	v_rcp_iflag_f32_e32 v2, v1
	s_sub_i32 s0, s12, s0
	s_sext_i32_i16 s0, s0
	s_add_i32 s13, s13, s0
	s_lshl_b32 s0, s13, 8
	v_mul_f32_e32 v2, v0, v2
	s_or_b32 s0, s0, s1
	v_trunc_f32_e32 v2, v2
	s_or_b32 s0, s0, 0x80200000
	v_fma_f32 v0, -v2, v1, v0
	v_cvt_i32_f32_e32 v2, v2
	s_and_b32 s0, s92, 7
	s_lshl_b32 s0, s0, 3
	s_bfe_u32 s1, s92, 0x30003
	s_add_i32 s0, s0, s1
	s_lshl_b32 s0, s0, 8
	s_lshr_b32 s1, s92, 6
	s_or_b32 s0, s0, s1
	s_or_b32 s0, s0, 0x80200000
	v_writelane_b32 v254, s0, 34
	s_ashr_i32 s0, s6, 30
	s_or_b32 s2, s0, 1
	v_cmp_ge_f32_e64 s[0:1], |v0|, v1
	s_and_b64 s[0:1], s[0:1], exec
	s_cselect_b32 s0, s2, 0
	v_readfirstlane_b32 s1, v2
	s_add_i32 s0, s1, s0
	s_sext_i32_i8 s1, s0
	s_mul_i32 s0, s0, s16
	s_sub_i32 s0, s6, s0
	s_sext_i32_i8 s0, s0
	s_add_i32 s9, s9, s0
	s_lshl_b32 s0, s9, 8
	s_or_b32 s0, s0, s1
	s_or_b32 s0, s0, 0x80080000
	v_writelane_b32 v254, s0, 35
	s_ashr_i32 s0, s10, 31
	v_writelane_b32 v254, s0, 36
	s_abs_i32 s0, s10
	v_writelane_b32 v254, s0, 37
	s_ashr_i32 s0, s11, 31
	v_writelane_b32 v254, s0, 38
	s_abs_i32 s0, s11
	v_writelane_b32 v254, s0, 39
	s_or_b32 s0, s8, 7
	v_writelane_b32 v254, s0, 40
	s_add_i32 s0, 0, 0x25ff0
	v_writelane_b32 v254, s0, 41
	s_add_i32 s0, 0, 0x25ff4
	v_writelane_b32 v254, s0, 42
	s_mov_b32 s2, 0
	v_writelane_b32 v254, s2, 43
	v_writelane_b32 v254, s4, 45
	s_movk_i32 s3, 0x1800
	s_mov_b32 s2, s92
	v_writelane_b32 v254, s5, 46
	v_writelane_b32 v254, s96, 47
	s_movk_i32 s66, 0x1080
	v_mov_b32_e32 v193, 0
	v_writelane_b32 v254, s97, 48
	v_writelane_b32 v254, s2, 49
	v_mov_b32_e32 v243, 1
	v_mov_b32_e32 v241, 0x358637bd
	v_writelane_b32 v254, s3, 50
	v_writelane_b32 v254, s94, 51
	s_mov_b32 s68, 0x800000
	s_mov_b32 s79, 0xc00000
	s_movk_i32 s91, 0x1000
	s_mov_b32 s1, 0x42b504f3
	s_mov_b32 s0, 0x1c8ff000
	s_mov_b32 s67, 0x1c07f000
	s_mov_b32 s61, 0x1c907000
	s_mov_b32 s64, 0x1c087000
	s_mov_b32 s69, 0x42ddb3d8
	s_mov_b32 s38, 0x2048f000
	s_mov_b32 s39, 0x1eb1f000
	s_mov_b32 s63, 0x2049f000
	s_mov_b32 s82, 0x1eb37000
	s_mov_b64 s[74:75], 0x20000
	s_mov_b32 s76, 0x3e0293ee
	s_mov_b32 s78, 0x3dd53b94
	s_mov_b64 s[80:81], 0x30000
	s_mov_b32 s41, 0
	v_writelane_b32 v254, s90, 52
	s_waitcnt lgkmcnt(0)
	s_barrier
	s_branch .LBB0_254
